# v119 + one static s_setprio 1 for waves 4-7 during the hand-written global attention loop (reset at loop exit); placement unchanged
# baseline (speedup 1.0000x reference)
; #define ATT_LAS __attribute__((address_space(3)))
; #define ATT_LDK(dst, buf) do { _Pragma("unroll") for (int d0_ = 0; d0_ < 4; ++d0_) { dst[2 * d0_] = *(const ATT_LAS bf16x8*)((buf) + kfrag + d0_ * 2048); dst[2 * d0_ + 1] = *(const ATT_LAS bf16x8*)((buf) + kfrag + d0_ * 2048 + 512); } } while (0)
; template <bool NOMAX> ...
;     ...
;         u32x4 kreg, vreg; bf16x8 kf[8]; f32x16 c0, c1, e0, e1;
;         { const u32x4 k0 = *(const u32x4*)(kg + (size_t)ATT_TROW(0) * PITCH), k1 = *(const u32x4*)(kg + (size_t)ATT_TROW(1) * PITCH);
;           *(ATT_LAS u32x4*)(ATT_KBUF(0) + koff) = k0; *(ATT_LAS u32x4*)(ATT_KBUF(1) + koff) = k1; }
;         __syncthreads();
;         kreg = *(const u32x4*)(kg + (size_t)ATT_TROW(2) * PITCH); vreg = *(const u32x4*)(vg + (size_t)ATT_TROW(0) * PITCH);
;         ATT_LDK(kf, ATT_KBUF(0));
;         c0 = (f32x16){}; c1 = (f32x16){};
; #pragma unroll
;         for (int d0 = 0; d0 < 4; ++d0) { c0 = __builtin_amdgcn_mfma_f32_32x32x16_bf16(kf[2 * d0], qf[d0], c0, 0, 0, 0); c1 = __builtin_amdgcn_mfma_f32_32x32x16_bf16(kf[2 * d0 + 1], qf[d0], c1, 0, 0, 0); }
;         m = NOMAX ? 0.f : rowmax32(c0, c1);
; #pragma unroll
;         for (int r = 0; r < 16; ++r) { e0[r] = __builtin_amdgcn_exp2f(c0[r] - m); e1[r] = __builtin_amdgcn_exp2f(c1[r] - m); }
;         ATT_LDK(kf, ATT_KBUF(1));
;         *(ATT_LAS u32x4*)(ATT_KBUF(2) + koff) = kreg; *(ATT_LAS u32x4*)(ATT_VBUF(0) + voff) = vreg;
;         __syncthreads();
;         u32x4 kregB = kreg, vregB = vreg;
;         kreg = *(const u32x4*)(kg + (size_t)ATT_TROW(3) * PITCH); vreg = *(const u32x4*)(vg + (size_t)ATT_TROW(1) * PITCH);
; __device__ __forceinline__ void attn_unit(int uv, const float* sink_l, const bf16_t* P, bf16_t* Y, ATT_LAS unsigned char* lds, const float* rpb_l, const float* qn_l, const float* kn_l) {
;     ...
;     float m, lsum = 0.f; f32x16 o0 = {}, o1 = {};
.Lmk_entry_g:
	v_mov_b32_e32 v202, 0
	v_mov_b32_e32 v124, 0
	v_mov_b32_e32 v204, 0
	v_mov_b32_e32 v205, 0
	v_mov_b32_e32 v208, 0
	v_mov_b32_e32 v209, 0
	v_mov_b32_e32 v0, 0
	v_mov_b32_e32 v1, 0
	v_mov_b32_e32 v2, 0
	v_mov_b32_e32 v3, 0
	v_mov_b32_e32 v4, 0
	v_mov_b32_e32 v5, 0
	v_mov_b32_e32 v6, 0
	v_mov_b32_e32 v7, 0
	v_mov_b32_e32 v8, 0
	v_mov_b32_e32 v9, 0
	v_mov_b32_e32 v10, 0
	v_mov_b32_e32 v11, 0
	v_mov_b32_e32 v12, 0
	v_mov_b32_e32 v13, 0
	v_mov_b32_e32 v14, 0
	v_mov_b32_e32 v15, 0
	v_mov_b32_e32 v16, 0
	v_mov_b32_e32 v17, 0
	v_mov_b32_e32 v18, 0
	v_mov_b32_e32 v19, 0
	v_mov_b32_e32 v20, 0
	v_mov_b32_e32 v21, 0
	v_mov_b32_e32 v22, 0
	v_mov_b32_e32 v23, 0
	v_mov_b32_e32 v24, 0
	v_mov_b32_e32 v25, 0
	v_mov_b32_e32 v26, 0
	v_mov_b32_e32 v27, 0
	v_mov_b32_e32 v28, 0
	v_mov_b32_e32 v29, 0
	v_mov_b32_e32 v30, 0
	v_mov_b32_e32 v31, 0
	s_lshl_b32 s92, s93, 6
	s_add_i32 s84, s27, s92
	v_lshrrev_b32_e32 v116, 6, v192
	v_and_b32_e32 v117, 63, v192
	v_lshrrev_b32_e32 v118, 3, v117
	v_sub_u32_e32 v118, v118, v116
	v_mul_i32_i24_e32 v248, 0x8ff0, v118
	v_and_b32_e32 v118, 3, v116
	v_lshlrev_b32_e32 v118, 4, v118
	v_lshlrev_b32_e32 v119, 3, v116
	v_sub_u32_e32 v118, v118, v119
	v_bfe_u32 v119, v117, 3, 1
	v_bfe_u32 v242, v117, 4, 1
	v_bfe_u32 v243, v117, 5, 1
	v_add_u32_e32 v242, v119, v242
	v_lshl_add_u32 v242, v243, 1, v242
	v_lshl_add_u32 v118, v242, 1, v118
	v_lshrrev_b32_e32 v243, 2, v116
	v_sub_u32_e32 v243, v243, v119
	v_mul_i32_i24_e32 v118, 0x1200, v118
	v_lshl_add_u32 v249, v243, 6, v118
	v_readfirstlane_b32 s100, v116
	s_mov_b64 s[98:99], 0x48000
	s_lshl_b32 s100, s100, 10
	s_cmp_lt_u32 s100, 0x1000
	s_cbranch_scc1 .Lg_noprio
	s_setprio 1
.Lg_noprio:
	v_add_u32_e32 v253, s35, v231
	v_mad_i64_i32 v[244:245], s[80:81], s30, v215, v[198:199]
	v_ashrrev_i32_e32 v243, 31, v248
	v_mov_b32_e32 v242, v248
	v_lshl_add_u64 v[244:245], v[242:243], 0, v[244:245]
	v_mad_i64_i32 v[246:247], s[80:81], s30, v215, v[200:201]
	v_ashrrev_i32_e32 v243, 31, v249
	v_mov_b32_e32 v242, v249
	v_lshl_add_u64 v[246:247], v[242:243], 0, v[246:247]
	s_add_i32 s71, s71, 4
	s_add_i32 s81, s100, 0x0
	s_mov_b32 m0, s81
	s_nop 0
	global_load_lds_dwordx4 v[244:245], off
	v_lshl_add_u64 v[244:245], v[244:245], 0, s[98:99]
	s_add_i32 s81, s100, 0x2000
	s_mov_b32 m0, s81
	s_nop 0
	global_load_lds_dwordx4 v[244:245], off
	v_lshl_add_u64 v[244:245], v[244:245], 0, s[98:99]
	s_add_i32 s81, s100, 0x4000
	s_mov_b32 m0, s81
	s_nop 0
	global_load_lds_dwordx4 v[244:245], off
	v_lshl_add_u64 v[244:245], v[244:245], 0, s[98:99]
	s_add_i32 s81, s100, 0x6000
	s_mov_b32 m0, s81
	s_nop 0
	global_load_lds_dwordx4 v[246:247], off
	v_lshl_add_u64 v[246:247], v[246:247], 0, s[98:99]
	s_waitcnt vmcnt(0)
	s_waitcnt lgkmcnt(0)
	s_barrier
	s_mov_b32 s96, 3
	s_cmp_lg_u32 s96, 4
	s_cbranch_scc1 .Lgp_ks
	v_mad_i64_i32 v[244:245], s[80:81], s84, v215, v[198:199]
	v_ashrrev_i32_e32 v243, 31, v248
	v_mov_b32_e32 v242, v248
	v_lshl_add_u64 v[244:245], v[242:243], 0, v[244:245]

; template <bool NOMAX> ...
;     ...
;         for (int t = 1; t < NF; t += 2) {
;             ATT_STEP(t, kreg, vreg, kregB, vregB, e0, e1, c0, c1);
;             if (t + 1 < NF) ATT_STEP(t + 1, kregB, vregB, kreg, vreg, c0, c1, e0, e1);
;         }
;         if ((NF - 1) & 1) { e0 = c0; e1 = c1; }
;     ...
;         { u32x4 pw[4]; float sacc = 0.f;
; #pragma unroll
;           for (int r = 0; r < 16; ++r) sacc += e0[r] + e1[r];
;           lsum += sacc;
.Lg_done:
	s_setprio 0
	v_add_f32_e32 v204, v204, v205
	v_add_f32_e32 v208, v208, v209
	v_add_f32_e32 v124, v204, v208
	s_waitcnt lgkmcnt(0)
	s_barrier
	s_branch .LBB0_535
	s_nop 0
	s_nop 0
	s_nop 0
	s_nop 0
	s_nop 0
	s_nop 0
	s_nop 0
	s_nop 0
	s_nop 0
	s_nop 0
	s_nop 0
	s_nop 0
	s_nop 0
	s_nop 0
	s_nop 0
	s_nop 0
	s_nop 0
	s_nop 0
	s_nop 0
	s_nop 0
	s_nop 0
	s_nop 0
	s_nop 0
	s_nop 0
	s_nop 0
	s_nop 0
	s_nop 0
	s_nop 0
	s_nop 0
	s_nop 0
	s_nop 0
	s_nop 0
	s_nop 0
	s_nop 0
	s_nop 0
	s_nop 0
	s_nop 0
	s_nop 0
	s_nop 0
	s_nop 0
	s_nop 0
	s_nop 0
	s_nop 0
	s_nop 0
	s_nop 0
	s_nop 0
	s_nop 0
	s_nop 0
	s_nop 0
	s_nop 0
	s_nop 0
